# weights + projection biases prepared layer by layer: layer l+1 transposed and its bias rows computed by the non-latent WGs at the end of scan phase l (own barrier between), phase 0 / pre only prepare
# baseline (speedup 1.0000x reference)
.Lg4_ret:
	v_readlane_b32 s58, v224, 36
	v_readlane_b32 s59, v227, 0
	s_movk_i32 s60, 0xb78
	s_mov_b32 s61, 0
	s_nop 0
	s_cmp_eq_u32 s58, 3
	s_cselect_b32 s60, 0, s60
	s_add_i32 s58, s58, 1
	s_add_i32 s59, s59, 0xffffff80
	s_movk_i32 s38, 0x180

.Ltr_loop:
	s_cmp_ge_u32 s59, s60
	s_cbranch_scc1 .Ltr_done
	s_mov_b32 s2, s59
	s_mov_b32 s3, s58

.Ltr0_z:
	s_lshr_b32 s65, s21, 7
	s_lshl_b32 s65, s65, 6
	s_bfe_u32 s20, s21, 0x10006
	s_lshl_b32 s20, s20, 5
	s_add_i32 s65, s65, s20
	s_cmp_lg_u64 s[72:73], 0
	s_cselect_b32 s65, s65, s21
	s_mul_i32 s20, s64, s66
	s_add_i32 s65, s65, s20
	s_lshl_b32 s65, s65, 2
	s_add_u32 s65, s65, s49
	s_mul_i32 s20, s21, s67
	s_add_i32 s20, s20, s64
	s_lshl_b32 s20, s20, 1
	s_add_u32 s20, s20, s57
	s_mov_b32 s21, s48
	s_mov_b32 s64, s56
	s_load_dwordx2 s[48:49], s[100:101], s21
	s_load_dwordx2 s[56:57], s[100:101], s64
	v_cndmask_b32_e64 v12, v2, v4, s[72:73]
	v_mul_lo_u32 v13, v3, s66
	v_add_lshl_u32 v10, v13, v12, 2
	v_mul_lo_u32 v13, v7, s67
	v_lshl_add_u32 v14, v13, 1, v8
	s_lshl_b32 s21, s66, 4
	s_waitcnt lgkmcnt(0)
	s_add_u32 s48, s48, s65
	s_addc_u32 s49, s49, 0
	s_add_u32 s56, s56, s20
	s_addc_u32 s57, s57, 0
	global_load_dword v20, v10, s[48:49]
	v_add_u32_e32 v10, s21, v10
	global_load_dword v21, v10, s[48:49]
	v_add_u32_e32 v10, s21, v10
	global_load_dword v22, v10, s[48:49]
	v_add_u32_e32 v10, s21, v10
	global_load_dword v23, v10, s[48:49]
	v_add_u32_e32 v10, s21, v10
	global_load_dword v24, v10, s[48:49]
	v_add_u32_e32 v10, s21, v10
	global_load_dword v25, v10, s[48:49]
	v_add_u32_e32 v10, s21, v10
	global_load_dword v26, v10, s[48:49]
	v_add_u32_e32 v10, s21, v10
	global_load_dword v27, v10, s[48:49]
	v_add_u32_e32 v10, s21, v10
	global_load_dword v28, v10, s[48:49]
	v_add_u32_e32 v10, s21, v10
	global_load_dword v29, v10, s[48:49]
	v_add_u32_e32 v10, s21, v10
	global_load_dword v30, v10, s[48:49]
	v_add_u32_e32 v10, s21, v10
	global_load_dword v31, v10, s[48:49]
	v_add_u32_e32 v10, s21, v10
	global_load_dword v32, v10, s[48:49]
	v_add_u32_e32 v10, s21, v10
	global_load_dword v33, v10, s[48:49]
	v_add_u32_e32 v10, s21, v10
	global_load_dword v34, v10, s[48:49]
	v_add_u32_e32 v10, s21, v10
	global_load_dword v35, v10, s[48:49]
	s_add_i32 s59, s59, s38
	s_cmp_ge_u32 s59, s60
	s_cselect_b32 s39, 0, 1
	s_cbranch_scc1 .Ltr_nosec
	s_mov_b32 s2, s59
	s_mov_b32 s3, s58

.Ltr_done:
	s_waitcnt vmcnt(0)
	s_cmp_eq_u32 s61, 0
	s_cbranch_scc0 .Ltr_ret_prep
	s_waitcnt vmcnt(0) lgkmcnt(0)
	s_barrier
	v_cmp_eq_u32_e32 vcc, 0, v131
	s_and_saveexec_b64 s[64:65], vcc
	s_cbranch_execz .Lsc_done
	s_load_dwordx2 s[2:3], s[100:101], 0x1f8
	buffer_wbl2 sc1
	s_waitcnt vmcnt(0) lgkmcnt(0)
	v_mov_b32_e32 v2, 1
	global_atomic_add v1, v2, s[2:3] offset:260
	s_mul_i32 s20, s58, 0x180
	s_mov_b32 s21, 0x40000
.Lsc_spin:
	s_sleep 1
	global_load_dword v2, v1, s[2:3] offset:260 sc1
	s_waitcnt vmcnt(0)
	v_readfirstlane_b32 s39, v2
	s_sub_u32 s21, s21, 1
	s_cmp_eq_u32 s21, 0
	s_cbranch_scc1 .Lsc_out
	s_cmp_lt_u32 s39, s20
	s_cbranch_scc1 .Lsc_spin

.Lsc_done:
	s_or_b64 exec, exec, s[64:65]
	s_barrier
	s_cmp_gt_u32 s58, 3
	s_cbranch_scc1 .Ltr_ret_scan
	s_load_dwordx2 s[48:49], s[100:101], 0x100
	s_load_dwordx2 s[56:57], s[100:101], 0x110
	s_load_dwordx2 s[84:85], s[100:101], 0x1b0
	s_load_dwordx2 s[92:93], s[100:101], 0x210
	s_load_dwordx2 s[72:73], s[100:101], 0x218
	v_readlane_b32 s59, v227, 0
	v_readfirstlane_b32 s60, v131
	s_nop 0
	s_add_i32 s59, s59, 0xffffff80
	s_lshl_b32 s59, s59, 2
	s_lshr_b32 s60, s60, 6
	s_add_i32 s59, s59, s60
	s_movk_i32 s60, 0x1e80
	v_and_b32_e32 v2, 63, v131
	v_lshlrev_b32_e32 v3, 6, v2
	v_lshlrev_b32_e32 v2, 5, v2
	v_add_u32_e32 v4, 0x6000, v3
	v_add_u32_e32 v5, 0xc000, v3
	v_add_u32_e32 v6, 0x12000, v3
	v_add_u32_e32 v7, 0x18000, v3
	s_waitcnt lgkmcnt(0)
	s_mul_i32 s20, s58, 0x440000
	s_add_u32 s48, s48, s20
	s_addc_u32 s49, s49, 0
	s_mul_i32 s20, s58, 0xb00000
	s_add_u32 s56, s56, s20
	s_addc_u32 s57, s57, 0
	s_mul_i32 s20, s58, 0x1e000
	s_add_u32 s84, s84, s20
	s_addc_u32 s85, s85, 0
	s_mul_i32 s20, s58, 0xaa00
	s_add_u32 s92, s92, s20
	s_addc_u32 s93, s93, 0
	s_mul_i32 s20, s58, 0x1b800
	s_add_u32 s72, s72, s20
	s_addc_u32 s73, s73, 0
.Lb_loop:
	s_cmp_ge_u32 s59, s60
	s_cbranch_scc1 .Ltr_ret_scan
	s_cmpk_ge_u32 s59, 0x880
	s_cbranch_scc1 .Lb_ffn
	s_lshl_b32 s66, s59, 11
	s_add_u32 s2, s48, s66
	s_addc_u32 s3, s49, 0
	s_mov_b64 s[20:21], s[84:85]
	s_lshl_b32 s66, s59, 2
	s_add_u32 s64, s92, s66
	s_addc_u32 s65, s93, 0
	s_movk_i32 s39, 0x2200
	s_branch .Lb_go
.Lb_ffn:
	s_sub_i32 s67, s59, 0x880
	s_lshl_b32 s66, s67, 11
	s_add_u32 s2, s56, s66
	s_addc_u32 s3, s57, 0
	s_add_u32 s20, s84, 0x3000
	s_addc_u32 s21, s85, 0
	s_lshl_b32 s66, s67, 2
	s_add_u32 s64, s72, s66
	s_addc_u32 s65, s73, 0
	s_movk_i32 s39, 0x5800
.Lb_go:
	global_load_dwordx4 v[10:13], v2, s[2:3]
	global_load_dwordx4 v[14:17], v2, s[2:3] offset:16
	global_load_dwordx4 v[40:43], v3, s[20:21] offset:0
	global_load_dwordx4 v[44:47], v3, s[20:21] offset:16
	global_load_dwordx4 v[48:51], v3, s[20:21] offset:32
	global_load_dwordx4 v[52:55], v3, s[20:21] offset:48
	global_load_dwordx4 v[56:59], v4, s[20:21] offset:0
	global_load_dwordx4 v[60:63], v4, s[20:21] offset:16
	global_load_dwordx4 v[64:67], v4, s[20:21] offset:32
	global_load_dwordx4 v[68:71], v4, s[20:21] offset:48
	global_load_dwordx4 v[72:75], v5, s[20:21] offset:0
	global_load_dwordx4 v[76:79], v5, s[20:21] offset:16
	global_load_dwordx4 v[80:83], v5, s[20:21] offset:32
	global_load_dwordx4 v[84:87], v5, s[20:21] offset:48
	global_load_dwordx4 v[88:91], v6, s[20:21] offset:0
	global_load_dwordx4 v[92:95], v6, s[20:21] offset:16
	global_load_dwordx4 v[96:99], v6, s[20:21] offset:32
	global_load_dwordx4 v[100:103], v6, s[20:21] offset:48
	global_load_dwordx4 v[104:107], v7, s[20:21] offset:0
	global_load_dwordx4 v[108:111], v7, s[20:21] offset:16
	global_load_dwordx4 v[112:115], v7, s[20:21] offset:32
	global_load_dwordx4 v[116:119], v7, s[20:21] offset:48
	s_waitcnt vmcnt(0)
	v_lshrrev_b32_e32 v18, 16, v10
	v_cvt_f32_f16_e32 v20, v10
	v_cvt_f32_f16_e32 v21, v18
	v_lshrrev_b32_e32 v18, 16, v11
	v_cvt_f32_f16_e32 v22, v11
	v_cvt_f32_f16_e32 v23, v18
	v_lshrrev_b32_e32 v18, 16, v12
	v_cvt_f32_f16_e32 v24, v12
	v_cvt_f32_f16_e32 v25, v18
	v_lshrrev_b32_e32 v18, 16, v13
	v_cvt_f32_f16_e32 v26, v13
	v_cvt_f32_f16_e32 v27, v18
	v_lshrrev_b32_e32 v18, 16, v14
	v_cvt_f32_f16_e32 v28, v14
	v_cvt_f32_f16_e32 v29, v18
	v_lshrrev_b32_e32 v18, 16, v15
	v_cvt_f32_f16_e32 v30, v15
	v_cvt_f32_f16_e32 v31, v18
	v_lshrrev_b32_e32 v18, 16, v16
	v_cvt_f32_f16_e32 v32, v16
	v_cvt_f32_f16_e32 v33, v18
	v_lshrrev_b32_e32 v18, 16, v17
	v_cvt_f32_f16_e32 v34, v17
	v_cvt_f32_f16_e32 v35, v18
	v_mul_f32_e32 v120, v40, v20
	v_fmac_f32_e32 v120, v41, v21
	v_fmac_f32_e32 v120, v42, v22
	v_fmac_f32_e32 v120, v43, v23
	v_fmac_f32_e32 v120, v44, v24
	v_fmac_f32_e32 v120, v45, v25
	v_fmac_f32_e32 v120, v46, v26
	v_fmac_f32_e32 v120, v47, v27
	v_fmac_f32_e32 v120, v48, v28
	v_fmac_f32_e32 v120, v49, v29
	v_fmac_f32_e32 v120, v50, v30
	v_fmac_f32_e32 v120, v51, v31
	v_fmac_f32_e32 v120, v52, v32
	v_fmac_f32_e32 v120, v53, v33
	v_fmac_f32_e32 v120, v54, v34
	v_fmac_f32_e32 v120, v55, v35
	v_mul_f32_e32 v121, v56, v20
	v_fmac_f32_e32 v121, v57, v21
	v_fmac_f32_e32 v121, v58, v22
	v_fmac_f32_e32 v121, v59, v23
	v_fmac_f32_e32 v121, v60, v24
	v_fmac_f32_e32 v121, v61, v25
	v_fmac_f32_e32 v121, v62, v26
	v_fmac_f32_e32 v121, v63, v27
	v_fmac_f32_e32 v121, v64, v28
	v_fmac_f32_e32 v121, v65, v29
	v_fmac_f32_e32 v121, v66, v30
	v_fmac_f32_e32 v121, v67, v31
	v_fmac_f32_e32 v121, v68, v32
	v_fmac_f32_e32 v121, v69, v33
	v_fmac_f32_e32 v121, v70, v34
	v_fmac_f32_e32 v121, v71, v35
	v_mul_f32_e32 v122, v72, v20
	v_fmac_f32_e32 v122, v73, v21
	v_fmac_f32_e32 v122, v74, v22
	v_fmac_f32_e32 v122, v75, v23
	v_fmac_f32_e32 v122, v76, v24
	v_fmac_f32_e32 v122, v77, v25
	v_fmac_f32_e32 v122, v78, v26
	v_fmac_f32_e32 v122, v79, v27
	v_fmac_f32_e32 v122, v80, v28
	v_fmac_f32_e32 v122, v81, v29
	v_fmac_f32_e32 v122, v82, v30
	v_fmac_f32_e32 v122, v83, v31
	v_fmac_f32_e32 v122, v84, v32
	v_fmac_f32_e32 v122, v85, v33
	v_fmac_f32_e32 v122, v86, v34
	v_fmac_f32_e32 v122, v87, v35
	v_mul_f32_e32 v123, v88, v20
	v_fmac_f32_e32 v123, v89, v21
	v_fmac_f32_e32 v123, v90, v22
	v_fmac_f32_e32 v123, v91, v23
	v_fmac_f32_e32 v123, v92, v24
	v_fmac_f32_e32 v123, v93, v25
	v_fmac_f32_e32 v123, v94, v26
	v_fmac_f32_e32 v123, v95, v27
	v_fmac_f32_e32 v123, v96, v28
	v_fmac_f32_e32 v123, v97, v29
	v_fmac_f32_e32 v123, v98, v30
	v_fmac_f32_e32 v123, v99, v31
	v_fmac_f32_e32 v123, v100, v32
	v_fmac_f32_e32 v123, v101, v33
	v_fmac_f32_e32 v123, v102, v34
	v_fmac_f32_e32 v123, v103, v35
	v_mul_f32_e32 v124, v104, v20
	v_fmac_f32_e32 v124, v105, v21
	v_fmac_f32_e32 v124, v106, v22
	v_fmac_f32_e32 v124, v107, v23
	v_fmac_f32_e32 v124, v108, v24
	v_fmac_f32_e32 v124, v109, v25
	v_fmac_f32_e32 v124, v110, v26
	v_fmac_f32_e32 v124, v111, v27
	v_fmac_f32_e32 v124, v112, v28
	v_fmac_f32_e32 v124, v113, v29
	v_fmac_f32_e32 v124, v114, v30
	v_fmac_f32_e32 v124, v115, v31
	v_fmac_f32_e32 v124, v116, v32
	v_fmac_f32_e32 v124, v117, v33
	v_fmac_f32_e32 v124, v118, v34
	v_fmac_f32_e32 v124, v119, v35
	s_nop 1
	v_add_f32_dpp v120, v120, v120 quad_perm:[1,0,3,2] row_mask:0xf bank_mask:0xf bound_ctrl:1
	v_add_f32_dpp v121, v121, v121 quad_perm:[1,0,3,2] row_mask:0xf bank_mask:0xf bound_ctrl:1
	v_add_f32_dpp v122, v122, v122 quad_perm:[1,0,3,2] row_mask:0xf bank_mask:0xf bound_ctrl:1
	v_add_f32_dpp v123, v123, v123 quad_perm:[1,0,3,2] row_mask:0xf bank_mask:0xf bound_ctrl:1
	v_add_f32_dpp v124, v124, v124 quad_perm:[1,0,3,2] row_mask:0xf bank_mask:0xf bound_ctrl:1
	s_nop 1
	v_add_f32_dpp v120, v120, v120 quad_perm:[2,3,0,1] row_mask:0xf bank_mask:0xf bound_ctrl:1
	v_add_f32_dpp v121, v121, v121 quad_perm:[2,3,0,1] row_mask:0xf bank_mask:0xf bound_ctrl:1
	v_add_f32_dpp v122, v122, v122 quad_perm:[2,3,0,1] row_mask:0xf bank_mask:0xf bound_ctrl:1
	v_add_f32_dpp v123, v123, v123 quad_perm:[2,3,0,1] row_mask:0xf bank_mask:0xf bound_ctrl:1
	v_add_f32_dpp v124, v124, v124 quad_perm:[2,3,0,1] row_mask:0xf bank_mask:0xf bound_ctrl:1
	s_nop 1
	v_add_f32_dpp v120, v120, v120 row_half_mirror row_mask:0xf bank_mask:0xf bound_ctrl:1
	v_add_f32_dpp v121, v121, v121 row_half_mirror row_mask:0xf bank_mask:0xf bound_ctrl:1
	v_add_f32_dpp v122, v122, v122 row_half_mirror row_mask:0xf bank_mask:0xf bound_ctrl:1
	v_add_f32_dpp v123, v123, v123 row_half_mirror row_mask:0xf bank_mask:0xf bound_ctrl:1
	v_add_f32_dpp v124, v124, v124 row_half_mirror row_mask:0xf bank_mask:0xf bound_ctrl:1
	s_nop 1
	v_add_f32_dpp v120, v120, v120 row_mirror row_mask:0xf bank_mask:0xf bound_ctrl:1
	v_add_f32_dpp v121, v121, v121 row_mirror row_mask:0xf bank_mask:0xf bound_ctrl:1
	v_add_f32_dpp v122, v122, v122 row_mirror row_mask:0xf bank_mask:0xf bound_ctrl:1
	v_add_f32_dpp v123, v123, v123 row_mirror row_mask:0xf bank_mask:0xf bound_ctrl:1
	v_add_f32_dpp v124, v124, v124 row_mirror row_mask:0xf bank_mask:0xf bound_ctrl:1
	s_nop 1
	v_readlane_b32 s66, v120, 0
	v_readlane_b32 s67, v120, 16
	v_readlane_b32 s14, v120, 32
	v_readlane_b32 s15, v120, 48
	s_nop 1
	v_mov_b32_e32 v125, s66
	v_add_f32_e32 v125, s67, v125
	v_add_f32_e32 v125, s14, v125
	v_add_f32_e32 v125, s15, v125
	v_readlane_b32 s66, v121, 0
	v_readlane_b32 s67, v121, 16
	v_readlane_b32 s14, v121, 32
	v_readlane_b32 s15, v121, 48
	s_nop 1
	v_mov_b32_e32 v126, s66
	v_add_f32_e32 v126, s67, v126
	v_add_f32_e32 v126, s14, v126
	v_add_f32_e32 v126, s15, v126
	v_readlane_b32 s66, v122, 0
	v_readlane_b32 s67, v122, 16
	v_readlane_b32 s14, v122, 32
	v_readlane_b32 s15, v122, 48
	s_nop 1
	v_mov_b32_e32 v127, s66
	v_add_f32_e32 v127, s67, v127
	v_add_f32_e32 v127, s14, v127
	v_add_f32_e32 v127, s15, v127
	v_readlane_b32 s66, v123, 0
	v_readlane_b32 s67, v123, 16
	v_readlane_b32 s14, v123, 32
	v_readlane_b32 s15, v123, 48
	s_nop 1
	v_mov_b32_e32 v128, s66
	v_add_f32_e32 v128, s67, v128
	v_add_f32_e32 v128, s14, v128
	v_add_f32_e32 v128, s15, v128
	v_readlane_b32 s66, v124, 0
	v_readlane_b32 s67, v124, 16
	v_readlane_b32 s14, v124, 32
	v_readlane_b32 s15, v124, 48
	s_nop 1
	v_mov_b32_e32 v129, s66
	v_add_f32_e32 v129, s67, v129
	v_add_f32_e32 v129, s14, v129
	v_add_f32_e32 v129, s15, v129
	s_mov_b64 exec, 1
	global_store_dword v1, v125, s[64:65]
	s_add_u32 s64, s64, s39
	s_addc_u32 s65, s65, 0
	global_store_dword v1, v126, s[64:65]
	s_add_u32 s64, s64, s39
	s_addc_u32 s65, s65, 0
	global_store_dword v1, v127, s[64:65]
	s_add_u32 s64, s64, s39
	s_addc_u32 s65, s65, 0
	global_store_dword v1, v128, s[64:65]
	s_add_u32 s64, s64, s39
	s_addc_u32 s65, s65, 0
	global_store_dword v1, v129, s[64:65]
	s_mov_b64 exec, -1
	s_addk_i32 s59, 0x600
	s_branch .Lb_loop

.LBB0_627:
	v_readlane_b32 s59, v227, 0
	s_mov_b32 s58, 0
	s_movk_i32 s60, 0xb78
	s_mov_b32 s61, 1
	s_movk_i32 s38, 0x200
	s_branch .Ltr_entry

.LBB0_888:
	s_or_b64 exec, exec, s[2:3]
	s_movk_i32 s2, 0x1e80
	v_cmp_gt_i32_e32 vcc, s2, v10
	s_and_saveexec_b64 s[2:3], vcc
	s_cbranch_execz .LBB0_905
	v_readlane_b32 s8, v224, 34
	v_readlane_b32 s9, v224, 35
	s_load_dwordx2 s[6:7], s[8:9], 0x1b0
	s_load_dwordx4 s[44:47], s[8:9], 0x210
	v_lshlrev_b32_e32 v0, 6, v23
	v_cmp_lt_i32_e32 vcc, v151, v152
	v_cmp_eq_u32_e64 s[40:41], 0, v23
	s_waitcnt lgkmcnt(0)
	v_lshl_add_u64 v[12:13], s[6:7], 0, v[0:1]
	v_cndmask_b32_e32 v0, v150, v151, vcc
	v_cmp_lt_i32_e32 vcc, v153, v152
	v_lshlrev_b32_e32 v11, 2, v0
	s_mov_b64 s[6:7], 0
	v_cndmask_b32_e32 v0, v150, v153, vcc
	v_lshlrev_b32_e32 v22, 2, v0
	v_lshlrev_b32_e32 v0, 1, v2
	s_branch .LBB0_891
.LBB0_890:
	s_or_b64 exec, exec, s[8:9]
	v_readlane_b32 s8, v224, 14
	v_readlane_b32 s9, v224, 15
	s_nop 0
	v_add_u32_e32 v10, s8, v10
	s_movk_i32 s8, 0x1e7f
	v_cmp_lt_i32_e32 vcc, s8, v10
	s_or_b64 s[6:7], vcc, s[6:7]
	s_andn2_b64 exec, exec, s[6:7]
	s_cbranch_execz .LBB0_905
